# idle-slot weight conversion (sites 2,3) software-pipelined: next item's loads in flight while the previous item is transposed and stored
# speedup vs baseline: 1.0046x; 1.0046x over previous
.LBB0_565:
	s_waitcnt vmcnt(0)
	v_readlane_b32 s0, v254, 55
	v_readlane_b32 s46, v254, 57
	v_readlane_b32 s52, v254, 59
	v_readlane_b32 s54, v254, 62
	v_readlane_b32 s56, v255, 0
	v_readlane_b32 s58, v255, 2
	s_barrier
	v_readlane_b32 s2, v254, 54
	v_readlane_b32 s1, v254, 56
	v_readlane_b32 s47, v254, 58
	v_readlane_b32 s53, v254, 60
	v_readlane_b32 s45, v254, 61
	v_readlane_b32 s55, v254, 63
	v_readlane_b32 s57, v255, 1
	v_readlane_b32 s59, v255, 3
	s_cmp_lg_u32 s68, 6
	s_cbranch_scc1 .Lcv2_done
	s_cmp_lt_u32 s2, 128
	s_cbranch_scc1 .Lcv2_done
	s_waitcnt vmcnt(0)
	v_and_b32_e32 v90, 63, v137
	v_lshrrev_b32_e32 v89, 6, v137
	s_nop 0
	v_readfirstlane_b32 s100, v89
	v_and_b32_e32 v84, 31, v90
	v_lshrrev_b32_e32 v86, 5, v90
	v_and_b32_e32 v88, 7, v90
	v_lshrrev_b32_e32 v87, 3, v90
	v_lshlrev_b32_e32 v85, 5, v88
	s_mul_i32 s101, s100, 0x2100
	v_mul_u32_u24_e32 v89, 33, v86
	v_add_u32_e32 v89, v89, v84
	v_lshl_add_u32 v81, v89, 2, s101
	v_mul_u32_u24_e32 v89, 0x108, v88
	v_add_u32_e32 v89, v89, v87
	v_lshl_add_u32 v82, v89, 2, s101
	s_sub_i32 s15, s2, 128
	s_lshl_b32 s15, s15, 3
	s_add_i32 s15, s15, s100
	s_add_i32 s15, s15, 6400
	s_cmp_ge_u32 s15, 11136
	s_cbranch_scc1 .Lcv2_done
	s_mov_b32 s38, 0
	s_mov_b32 s39, 0

.Lcv2_pent:
	s_cmp_eq_u32 s38, 0
	s_cbranch_scc1 .Lcv2_noprev
	s_cmp_eq_u32 s34, 32
	s_cbranch_scc1 .Lcv2_nomask
	v_cmp_gt_u32_e32 vcc, s34, v84
	s_nop 1
	v_cndmask_b32_e32 v91, 0, v91, vcc
	v_cndmask_b32_e32 v92, 0, v92, vcc
	v_cndmask_b32_e32 v93, 0, v93, vcc
	v_cndmask_b32_e32 v94, 0, v94, vcc
	v_cndmask_b32_e32 v95, 0, v95, vcc
	v_cndmask_b32_e32 v96, 0, v96, vcc
	v_cndmask_b32_e32 v97, 0, v97, vcc
	v_cndmask_b32_e32 v98, 0, v98, vcc
	v_cndmask_b32_e32 v99, 0, v99, vcc
	v_cndmask_b32_e32 v100, 0, v100, vcc
	v_cndmask_b32_e32 v101, 0, v101, vcc
	v_cndmask_b32_e32 v102, 0, v102, vcc
	v_cndmask_b32_e32 v103, 0, v103, vcc
	v_cndmask_b32_e32 v104, 0, v104, vcc
	v_cndmask_b32_e32 v105, 0, v105, vcc
	v_cndmask_b32_e32 v106, 0, v106, vcc
	v_cndmask_b32_e32 v107, 0, v107, vcc
	v_cndmask_b32_e32 v108, 0, v108, vcc
	v_cndmask_b32_e32 v109, 0, v109, vcc
	v_cndmask_b32_e32 v110, 0, v110, vcc
	v_cndmask_b32_e32 v111, 0, v111, vcc
	v_cndmask_b32_e32 v112, 0, v112, vcc
	v_cndmask_b32_e32 v113, 0, v113, vcc
	v_cndmask_b32_e32 v114, 0, v114, vcc
	v_cndmask_b32_e32 v115, 0, v115, vcc
	v_cndmask_b32_e32 v116, 0, v116, vcc
	v_cndmask_b32_e32 v117, 0, v117, vcc
	v_cndmask_b32_e32 v118, 0, v118, vcc
	v_cndmask_b32_e32 v119, 0, v119, vcc
	v_cndmask_b32_e32 v120, 0, v120, vcc
	v_cndmask_b32_e32 v121, 0, v121, vcc
	v_cndmask_b32_e32 v122, 0, v122, vcc
.Lcv2_nomask:
	ds_write_b32 v81, v91
	ds_write_b32 v81, v92 offset:264
	ds_write_b32 v81, v93 offset:528
	ds_write_b32 v81, v94 offset:792
	ds_write_b32 v81, v95 offset:1056
	ds_write_b32 v81, v96 offset:1320
	ds_write_b32 v81, v97 offset:1584
	ds_write_b32 v81, v98 offset:1848
	ds_write_b32 v81, v99 offset:2112
	ds_write_b32 v81, v100 offset:2376
	ds_write_b32 v81, v101 offset:2640
	ds_write_b32 v81, v102 offset:2904
	ds_write_b32 v81, v103 offset:3168
	ds_write_b32 v81, v104 offset:3432
	ds_write_b32 v81, v105 offset:3696
	ds_write_b32 v81, v106 offset:3960
	ds_write_b32 v81, v107 offset:4224
	ds_write_b32 v81, v108 offset:4488
	ds_write_b32 v81, v109 offset:4752
	ds_write_b32 v81, v110 offset:5016
	ds_write_b32 v81, v111 offset:5280
	ds_write_b32 v81, v112 offset:5544
	ds_write_b32 v81, v113 offset:5808
	ds_write_b32 v81, v114 offset:6072
	ds_write_b32 v81, v115 offset:6336
	ds_write_b32 v81, v116 offset:6600
	ds_write_b32 v81, v117 offset:6864
	ds_write_b32 v81, v118 offset:7128
	ds_write_b32 v81, v119 offset:7392
	ds_write_b32 v81, v120 offset:7656
	ds_write_b32 v81, v121 offset:7920
	ds_write_b32 v81, v122 offset:8184
	ds_read2_b32 v[40:41], v82 offset1:33
	ds_read2_b32 v[42:43], v82 offset0:66 offset1:99
	ds_read2_b32 v[44:45], v82 offset0:132 offset1:165
	ds_read2_b32 v[46:47], v82 offset0:198 offset1:231
	ds_read2_b32 v[48:49], v82 offset0:8 offset1:41
	ds_read2_b32 v[50:51], v82 offset0:74 offset1:107
	ds_read2_b32 v[52:53], v82 offset0:140 offset1:173
	ds_read2_b32 v[54:55], v82 offset0:206 offset1:239
	ds_read2_b32 v[56:57], v82 offset0:16 offset1:49
	ds_read2_b32 v[58:59], v82 offset0:82 offset1:115
	ds_read2_b32 v[60:61], v82 offset0:148 offset1:181
	ds_read2_b32 v[62:63], v82 offset0:214 offset1:247
	ds_read2_b32 v[64:65], v82 offset0:24 offset1:57
	ds_read2_b32 v[66:67], v82 offset0:90 offset1:123
	ds_read2_b32 v[68:69], v82 offset0:156 offset1:189
	ds_read2_b32 v[70:71], v82 offset0:222 offset1:255
	s_waitcnt lgkmcnt(0)
	v_mul_f32_e32 v40, v123, v40
	v_mul_f32_e32 v41, v124, v41
	v_mul_f32_e32 v42, v125, v42
	v_mul_f32_e32 v43, v126, v43
	v_mul_f32_e32 v44, v127, v44
	v_mul_f32_e32 v45, v128, v45
	v_mul_f32_e32 v46, v129, v46
	v_mul_f32_e32 v47, v130, v47
	v_cvt_pk_bf16_f32 v72, v40, v41
	v_cvt_pk_bf16_f32 v73, v42, v43
	v_cvt_pk_bf16_f32 v74, v44, v45
	v_cvt_pk_bf16_f32 v75, v46, v47
	global_store_dwordx4 v131, v[72:75], s[36:37]
	v_add_u32_e32 v131, s35, v131
	v_mul_f32_e32 v48, v123, v48
	v_mul_f32_e32 v49, v124, v49
	v_mul_f32_e32 v50, v125, v50
	v_mul_f32_e32 v51, v126, v51
	v_mul_f32_e32 v52, v127, v52
	v_mul_f32_e32 v53, v128, v53
	v_mul_f32_e32 v54, v129, v54
	v_mul_f32_e32 v55, v130, v55
	v_cvt_pk_bf16_f32 v76, v48, v49
	v_cvt_pk_bf16_f32 v77, v50, v51
	v_cvt_pk_bf16_f32 v78, v52, v53
	v_cvt_pk_bf16_f32 v79, v54, v55
	global_store_dwordx4 v131, v[76:79], s[36:37]
	v_add_u32_e32 v131, s35, v131
	v_mul_f32_e32 v56, v123, v56
	v_mul_f32_e32 v57, v124, v57
	v_mul_f32_e32 v58, v125, v58
	v_mul_f32_e32 v59, v126, v59
	v_mul_f32_e32 v60, v127, v60
	v_mul_f32_e32 v61, v128, v61
	v_mul_f32_e32 v62, v129, v62
	v_mul_f32_e32 v63, v130, v63
	v_cvt_pk_bf16_f32 v72, v56, v57
	v_cvt_pk_bf16_f32 v73, v58, v59
	v_cvt_pk_bf16_f32 v74, v60, v61
	v_cvt_pk_bf16_f32 v75, v62, v63
	global_store_dwordx4 v131, v[72:75], s[36:37]
	v_add_u32_e32 v131, s35, v131
	v_mul_f32_e32 v64, v123, v64
	v_mul_f32_e32 v65, v124, v65
	v_mul_f32_e32 v66, v125, v66
	v_mul_f32_e32 v67, v126, v67
	v_mul_f32_e32 v68, v127, v68
	v_mul_f32_e32 v69, v128, v69
	v_mul_f32_e32 v70, v129, v70
	v_mul_f32_e32 v71, v130, v71
	v_cvt_pk_bf16_f32 v76, v64, v65
	v_cvt_pk_bf16_f32 v77, v66, v67
	v_cvt_pk_bf16_f32 v78, v68, v69
	v_cvt_pk_bf16_f32 v79, v70, v71
	global_store_dwordx4 v131, v[76:79], s[36:37]
.Lcv2_noprev:
	s_cmp_lg_u32 s39, 0
	s_cbranch_scc1 .Lcv2_done
	s_waitcnt vmcnt(0)
	v_mov_b32_e32 v91, v0
	v_mov_b32_e32 v92, v1
	v_mov_b32_e32 v93, v2
	v_mov_b32_e32 v94, v3
	v_mov_b32_e32 v95, v4
	v_mov_b32_e32 v96, v5
	v_mov_b32_e32 v97, v6
	v_mov_b32_e32 v98, v7
	v_mov_b32_e32 v99, v8
	v_mov_b32_e32 v100, v9
	v_mov_b32_e32 v101, v10
	v_mov_b32_e32 v102, v11
	v_mov_b32_e32 v103, v12
	v_mov_b32_e32 v104, v13
	v_mov_b32_e32 v105, v14
	v_mov_b32_e32 v106, v15
	v_mov_b32_e32 v107, v16
	v_mov_b32_e32 v108, v17
	v_mov_b32_e32 v109, v18
	v_mov_b32_e32 v110, v19
	v_mov_b32_e32 v111, v20
	v_mov_b32_e32 v112, v21
	v_mov_b32_e32 v113, v22
	v_mov_b32_e32 v114, v23
	v_mov_b32_e32 v115, v24
	v_mov_b32_e32 v116, v25
	v_mov_b32_e32 v117, v26
	v_mov_b32_e32 v118, v27
	v_mov_b32_e32 v119, v28
	v_mov_b32_e32 v120, v29
	v_mov_b32_e32 v121, v30
	v_mov_b32_e32 v122, v31
	v_mov_b32_e32 v123, v32
	v_mov_b32_e32 v124, v33
	v_mov_b32_e32 v125, v34
	v_mov_b32_e32 v126, v35
	v_mov_b32_e32 v127, v36
	v_mov_b32_e32 v128, v37
	v_mov_b32_e32 v129, v38
	v_mov_b32_e32 v130, v39
	v_mov_b32_e32 v131, v83
	s_mov_b32 s34, s23
	s_lshl_b32 s35, s31, 4
	s_mov_b64 s[36:37], s[28:29]
	s_mov_b32 s38, 1
	s_add_i32 s15, s15, 1024
	s_cmp_lt_u32 s15, 11136
	s_cbranch_scc1 .Lcv2_loop
	s_mov_b32 s39, 1
	s_branch .Lcv2_pent
.Lcv2_done:
	s_cmp_lg_u32 s68, 13
	s_cbranch_scc1 .Lcv3_done
	s_cmp_lt_u32 s2, 128
	s_cbranch_scc1 .Lcv3_done
	s_waitcnt vmcnt(0)
	v_and_b32_e32 v90, 63, v137
	v_lshrrev_b32_e32 v89, 6, v137
	s_nop 0
	v_readfirstlane_b32 s100, v89
	v_and_b32_e32 v84, 31, v90
	v_lshrrev_b32_e32 v86, 5, v90
	v_and_b32_e32 v88, 7, v90
	v_lshrrev_b32_e32 v87, 3, v90
	v_lshlrev_b32_e32 v85, 5, v88
	s_mul_i32 s101, s100, 0x2100
	v_mul_u32_u24_e32 v89, 33, v86
	v_add_u32_e32 v89, v89, v84
	v_lshl_add_u32 v81, v89, 2, s101
	v_mul_u32_u24_e32 v89, 0x108, v88
	v_add_u32_e32 v89, v89, v87
	v_lshl_add_u32 v82, v89, 2, s101
	s_sub_i32 s15, s2, 128
	s_lshl_b32 s15, s15, 3
	s_add_i32 s15, s15, s100
	s_add_i32 s15, s15, 11136
	s_cmp_ge_u32 s15, 12544
	s_cbranch_scc1 .Lcv3_done
	s_mov_b32 s38, 0
	s_mov_b32 s39, 0

.Lcv3_noprev:
	s_cmp_lg_u32 s39, 0
	s_cbranch_scc1 .Lcv3_done
	s_waitcnt vmcnt(0)
	v_mov_b32_e32 v91, v0
	v_mov_b32_e32 v92, v1
	v_mov_b32_e32 v93, v2
	v_mov_b32_e32 v94, v3
	v_mov_b32_e32 v95, v4
	v_mov_b32_e32 v96, v5
	v_mov_b32_e32 v97, v6
	v_mov_b32_e32 v98, v7
	v_mov_b32_e32 v99, v8
	v_mov_b32_e32 v100, v9
	v_mov_b32_e32 v101, v10
	v_mov_b32_e32 v102, v11
	v_mov_b32_e32 v103, v12
	v_mov_b32_e32 v104, v13
	v_mov_b32_e32 v105, v14
	v_mov_b32_e32 v106, v15
	v_mov_b32_e32 v107, v16
	v_mov_b32_e32 v108, v17
	v_mov_b32_e32 v109, v18
	v_mov_b32_e32 v110, v19
	v_mov_b32_e32 v111, v20
	v_mov_b32_e32 v112, v21
	v_mov_b32_e32 v113, v22
	v_mov_b32_e32 v114, v23
	v_mov_b32_e32 v115, v24
	v_mov_b32_e32 v116, v25
	v_mov_b32_e32 v117, v26
	v_mov_b32_e32 v118, v27
	v_mov_b32_e32 v119, v28
	v_mov_b32_e32 v120, v29
	v_mov_b32_e32 v121, v30
	v_mov_b32_e32 v122, v31
	v_mov_b32_e32 v123, v32
	v_mov_b32_e32 v124, v33
	v_mov_b32_e32 v125, v34
	v_mov_b32_e32 v126, v35
	v_mov_b32_e32 v127, v36
	v_mov_b32_e32 v128, v37
	v_mov_b32_e32 v129, v38
	v_mov_b32_e32 v130, v39
	v_mov_b32_e32 v131, v83
	s_mov_b32 s34, s23
	s_lshl_b32 s35, s31, 4
	s_mov_b64 s[36:37], s[28:29]
	s_mov_b32 s38, 1
	s_add_i32 s15, s15, 1024
	s_cmp_lt_u32 s15, 12544
	s_cbranch_scc1 .Lcv3_loop
	s_mov_b32 s39, 1
	s_branch .Lcv3_pent
